# removed 8 leftover s_nop in PV head of DF loop; otherwise as previous best
# baseline (speedup 1.0000x reference)
; #define SBAR() __builtin_amdgcn_sched_barrier(0)
; #define PV_RD(S, d0) do { constexpr int b_ = PV_OFF(d0); TRRD(S##l0, b_); TRRD(S##h0, b_ + 2048); TRRD(S##l1, b_ + 4096); TRRD(S##h1, b_ + 6144); TRRD(S##l2, b_ + 8192); TRRD(S##h2, b_ + 10240); TRRD(S##l3, b_ + 12288); TRRD(S##h3, b_ + 14336); } while (0)
; #define PV_W8() do { asm volatile("s_waitcnt lgkmcnt(8)" ::: "memory"); SBAR(); } while (0)
; #define PV_W0() do { asm volatile("s_waitcnt lgkmcnt(0)" ::: "memory"); SBAR(); } while (0)
; template <int ND0>
; __device__ __forceinline__ void pv_tile2(f32x16* o, unsigned vb, bf16x8 pa0, bf16x8 pa1, bf16x8 pa2, bf16x8 pa3) {
;     ...
;     s16x4 Al0, Al1, Al2, Al3, Ah0, Ah1, Ah2, Ah3, Bl0, Bl1, Bl2, Bl3, Bh0, Bh1, Bh2, Bh3;
;     PV_RD(A, 0);
;     PV_RD(B, 1); PV_W8(); PV_MM(A, 0); SBAR();
;     PV_RD(A, 2); PV_W8(); PV_MM(B, 1); SBAR();
;     if constexpr (ND0 > 4) {
;         PV_RD(B, 3); PV_W8(); PV_MM(A, 2); SBAR();
;         PV_RD(A, 4); PV_W8(); PV_MM(B, 3); SBAR();
;         PV_RD(B, 5); PV_W8(); PV_MM(A, 4); SBAR();
;         PV_RD(A, 6); PV_W8(); PV_MM(B, 5); SBAR();
;         PV_RD(B, 7); PV_W8(); PV_MM(A, 6); SBAR();
;         PV_W0(); PV_MM(B, 7);
; __device__ __forceinline__ void finishSM(f32x16& p0, f32x16& p1, float alpha, float& l_reg, bf16x8& pa0, bf16x8& pa1, bf16x8& pa2, bf16x8& pa3) {
;     ...
;     { auto rr = __builtin_amdgcn_permlane32_swap(__float_as_uint(ps), __float_as_uint(ps), false, false);
;       ps = __uint_as_float(rr[0]) + __uint_as_float(rr[1]); }
;     l_reg = l_reg * alpha + ps;
.Ldf_pv:
	v_add_u32_e32 v0, s4, v214
	ds_read_b64_tr_b16 v[146:147], v0 offset:0
	ds_read_b64_tr_b16 v[148:149], v0 offset:0x800
	ds_read_b64_tr_b16 v[150:151], v0 offset:0x1000
	ds_read_b64_tr_b16 v[152:153], v0 offset:0x1800
	v_mov_b32_e32 v210, v217
	ds_read_b64_tr_b16 v[154:155], v0 offset:0x2000
	s_nop 1
	v_permlane32_swap_b32_e32 v217, v210
	ds_read_b64_tr_b16 v[156:157], v0 offset:0x2800
	v_add_f32_e32 v217, v217, v210
	ds_read_b64_tr_b16 v[158:159], v0 offset:0x3000
	v_add_f32_e32 v216, v216, v217
	ds_read_b64_tr_b16 v[160:161], v0 offset:0x3800
	ds_read_b64_tr_b16 v[210:211], v0 offset:0x200
	ds_read_b64_tr_b16 v[212:213], v0 offset:0xa00
	ds_read_b64_tr_b16 v[218:219], v0 offset:0x1200
	ds_read_b64_tr_b16 v[220:221], v0 offset:0x1a00
	ds_read_b64_tr_b16 v[226:227], v0 offset:0x2200
	ds_read_b64_tr_b16 v[228:229], v0 offset:0x2a00
	ds_read_b64_tr_b16 v[234:235], v0 offset:0x3200
	ds_read_b64_tr_b16 v[236:237], v0 offset:0x3a00
	s_waitcnt lgkmcnt(8)
	v_mfma_f32_32x32x16_bf16 v[114:129], v[130:133], v[146:149], v[114:129]
	v_mfma_f32_32x32x16_bf16 v[114:129], v[134:137], v[150:153], v[114:129]
	v_mfma_f32_32x32x16_bf16 v[114:129], v[138:141], v[154:157], v[114:129]
	v_mfma_f32_32x32x16_bf16 v[114:129], v[142:145], v[158:161], v[114:129]
	ds_read_b64_tr_b16 v[146:147], v0 offset:0x400
	ds_read_b64_tr_b16 v[148:149], v0 offset:0xc00
	ds_read_b64_tr_b16 v[150:151], v0 offset:0x1400
	ds_read_b64_tr_b16 v[152:153], v0 offset:0x1c00
	ds_read_b64_tr_b16 v[154:155], v0 offset:0x2400
	ds_read_b64_tr_b16 v[156:157], v0 offset:0x2c00
	ds_read_b64_tr_b16 v[158:159], v0 offset:0x3400
	ds_read_b64_tr_b16 v[160:161], v0 offset:0x3c00
	s_waitcnt lgkmcnt(8)
	v_mfma_f32_32x32x16_bf16 v[98:113], v[130:133], v[210:213], v[98:113]
	v_mfma_f32_32x32x16_bf16 v[98:113], v[134:137], v[218:221], v[98:113]
	v_mfma_f32_32x32x16_bf16 v[98:113], v[138:141], v[226:229], v[98:113]
	v_mfma_f32_32x32x16_bf16 v[98:113], v[142:145], v[234:237], v[98:113]
	ds_read_b64_tr_b16 v[210:211], v0 offset:0x600
	ds_read_b64_tr_b16 v[212:213], v0 offset:0xe00
	ds_read_b64_tr_b16 v[218:219], v0 offset:0x1600
	ds_read_b64_tr_b16 v[220:221], v0 offset:0x1e00
	ds_read_b64_tr_b16 v[226:227], v0 offset:0x2600
	ds_read_b64_tr_b16 v[228:229], v0 offset:0x2e00
	ds_read_b64_tr_b16 v[234:235], v0 offset:0x3600
	ds_read_b64_tr_b16 v[236:237], v0 offset:0x3e00
	s_waitcnt lgkmcnt(8)
	v_mfma_f32_32x32x16_bf16 v[82:97], v[130:133], v[146:149], v[82:97]
	v_mfma_f32_32x32x16_bf16 v[82:97], v[134:137], v[150:153], v[82:97]
	v_mfma_f32_32x32x16_bf16 v[82:97], v[138:141], v[154:157], v[82:97]
	v_mfma_f32_32x32x16_bf16 v[82:97], v[142:145], v[158:161], v[82:97]
	ds_read_b64_tr_b16 v[146:147], v0 offset:0x4000
	ds_read_b64_tr_b16 v[148:149], v0 offset:0x4800
	ds_read_b64_tr_b16 v[150:151], v0 offset:0x5000
	ds_read_b64_tr_b16 v[152:153], v0 offset:0x5800
	ds_read_b64_tr_b16 v[154:155], v0 offset:0x6000
	ds_read_b64_tr_b16 v[156:157], v0 offset:0x6800
	ds_read_b64_tr_b16 v[158:159], v0 offset:0x7000
	ds_read_b64_tr_b16 v[160:161], v0 offset:0x7800
	s_waitcnt lgkmcnt(8)
	v_mfma_f32_32x32x16_bf16 v[66:81], v[130:133], v[210:213], v[66:81]
	v_mfma_f32_32x32x16_bf16 v[66:81], v[134:137], v[218:221], v[66:81]
	v_mfma_f32_32x32x16_bf16 v[66:81], v[138:141], v[226:229], v[66:81]
	v_mfma_f32_32x32x16_bf16 v[66:81], v[142:145], v[234:237], v[66:81]
	ds_read_b64_tr_b16 v[210:211], v0 offset:0x4200
	ds_read_b64_tr_b16 v[212:213], v0 offset:0x4a00
	ds_read_b64_tr_b16 v[218:219], v0 offset:0x5200
	ds_read_b64_tr_b16 v[220:221], v0 offset:0x5a00
	ds_read_b64_tr_b16 v[226:227], v0 offset:0x6200
	ds_read_b64_tr_b16 v[228:229], v0 offset:0x6a00
	ds_read_b64_tr_b16 v[234:235], v0 offset:0x7200
	ds_read_b64_tr_b16 v[236:237], v0 offset:0x7a00
	s_waitcnt lgkmcnt(8)
	v_mfma_f32_32x32x16_bf16 v[50:65], v[130:133], v[146:149], v[50:65]
	v_mfma_f32_32x32x16_bf16 v[50:65], v[134:137], v[150:153], v[50:65]
	v_mfma_f32_32x32x16_bf16 v[50:65], v[138:141], v[154:157], v[50:65]
	v_mfma_f32_32x32x16_bf16 v[50:65], v[142:145], v[158:161], v[50:65]
	ds_read_b64_tr_b16 v[146:147], v0 offset:0x4400
	ds_read_b64_tr_b16 v[148:149], v0 offset:0x4c00
	ds_read_b64_tr_b16 v[150:151], v0 offset:0x5400
	ds_read_b64_tr_b16 v[152:153], v0 offset:0x5c00
	ds_read_b64_tr_b16 v[154:155], v0 offset:0x6400
	ds_read_b64_tr_b16 v[156:157], v0 offset:0x6c00
	ds_read_b64_tr_b16 v[158:159], v0 offset:0x7400
	ds_read_b64_tr_b16 v[160:161], v0 offset:0x7c00
	s_waitcnt lgkmcnt(8)
	v_mfma_f32_32x32x16_bf16 v[34:49], v[130:133], v[210:213], v[34:49]
	v_mfma_f32_32x32x16_bf16 v[34:49], v[134:137], v[218:221], v[34:49]
	v_mfma_f32_32x32x16_bf16 v[34:49], v[138:141], v[226:229], v[34:49]
	v_mfma_f32_32x32x16_bf16 v[34:49], v[142:145], v[234:237], v[34:49]
	ds_read_b64_tr_b16 v[210:211], v0 offset:0x4600
	ds_read_b64_tr_b16 v[212:213], v0 offset:0x4e00
	ds_read_b64_tr_b16 v[218:219], v0 offset:0x5600
	ds_read_b64_tr_b16 v[220:221], v0 offset:0x5e00
	ds_read_b64_tr_b16 v[226:227], v0 offset:0x6600
	ds_read_b64_tr_b16 v[228:229], v0 offset:0x6e00
	ds_read_b64_tr_b16 v[234:235], v0 offset:0x7600
	ds_read_b64_tr_b16 v[236:237], v0 offset:0x7e00
	s_waitcnt lgkmcnt(8)
	v_mfma_f32_32x32x16_bf16 v[18:33], v[130:133], v[146:149], v[18:33]
	v_mfma_f32_32x32x16_bf16 v[18:33], v[134:137], v[150:153], v[18:33]
	v_mfma_f32_32x32x16_bf16 v[18:33], v[138:141], v[154:157], v[18:33]
	v_mfma_f32_32x32x16_bf16 v[18:33], v[142:145], v[158:161], v[18:33]
	s_waitcnt lgkmcnt(0)
	v_mfma_f32_32x32x16_bf16 v[2:17], v[130:133], v[210:213], v[2:17]
	v_mfma_f32_32x32x16_bf16 v[2:17], v[134:137], v[218:221], v[2:17]
	v_mfma_f32_32x32x16_bf16 v[2:17], v[138:141], v[226:229], v[2:17]
	v_mfma_f32_32x32x16_bf16 v[2:17], v[142:145], v[234:237], v[2:17]
